# hyena sample path: 23 filter taps per thread via batched branch-free global loads (was 24 serialized load+wait in divergent branches)
# speedup vs baseline: 1.0102x; 1.0061x over previous
.LBB0_573:
	s_or_b64 exec, exec, s[0:1]
	s_add_i32 s0, 0, 0x24880
	v_mov_b32_e32 v12, s0
	s_waitcnt lgkmcnt(0)
	s_barrier
	ds_read_b128 v[0:3], v12
	ds_read_b128 v[4:7], v12 offset:16
	ds_read_b128 v[8:11], v12 offset:32
	ds_read_b128 v[12:15], v12 offset:48
	s_mov_b32 s0, 0x358637bd
	s_waitcnt lgkmcnt(3)
	v_mov_b32_e32 v96, v0
	s_mov_b32 s4, 0
	s_waitcnt lgkmcnt(1)
	v_mov_b32_e32 v97, v8
	v_pk_add_f32 v[96:97], v[96:97], 0 op_sel_hi:[1,0]
	v_mov_b32_e32 v8, v1
	v_pk_add_f32 v[0:1], v[96:97], v[8:9]
	v_mov_b32_e32 v8, v2
	v_mov_b32_e32 v9, v10
	v_pk_add_f32 v[0:1], v[0:1], v[8:9]
	v_mov_b32_e32 v10, v3
	v_pk_add_f32 v[0:1], v[0:1], v[10:11]
	v_mov_b32_e32 v2, v4
	s_waitcnt lgkmcnt(0)
	v_mov_b32_e32 v3, v12
	v_pk_add_f32 v[0:1], v[0:1], v[2:3]
	v_mov_b32_e32 v12, v5
	v_pk_add_f32 v[0:1], v[0:1], v[12:13]
	v_mov_b32_e32 v2, v6
	v_mov_b32_e32 v3, v14
	v_pk_add_f32 v[0:1], v[0:1], v[2:3]
	v_mov_b32_e32 v14, v7
	v_pk_add_f32 v[0:1], v[0:1], v[14:15]
	s_movk_i32 s5, 0x5eed
	v_pk_add_f32 v[0:1], v[0:1], s[0:1] op_sel_hi:[1,0]
	s_mov_b32 s13, s4
	v_div_scale_f32 v2, s[0:1], v1, v1, 1.0
	v_rcp_f32_e32 v3, v2
	v_readlane_b32 s16, v254, 10
	v_readlane_b32 s22, v254, 16
	v_readlane_b32 s23, v254, 17
	v_fma_f32 v4, -v2, v3, 1.0
	v_fmac_f32_e32 v3, v4, v3
	v_div_scale_f32 v4, vcc, 1.0, v1, 1.0
	v_mul_f32_e32 v5, v4, v3
	v_fma_f32 v6, -v2, v5, v4
	v_fmac_f32_e32 v5, v6, v3
	v_fma_f32 v2, -v2, v5, v4
	v_div_fmas_f32 v2, v2, v3, v5
	v_div_fixup_f32 v1, v2, v1, 1.0
	v_div_scale_f32 v2, s[0:1], v0, v0, 1.0
	v_rcp_f32_e32 v3, v2
	s_lshl_b64 s[0:1], s[12:13], 2
	s_add_u32 s0, s22, s0
	s_addc_u32 s1, s23, s1
	v_fma_f32 v4, -v2, v3, 1.0
	v_fmac_f32_e32 v3, v4, v3
	v_div_scale_f32 v4, vcc, 1.0, v0, 1.0
	v_mul_f32_e32 v5, v4, v3
	v_fma_f32 v6, -v2, v5, v4
	v_fmac_f32_e32 v5, v6, v3
	v_fma_f32 v2, -v2, v5, v4
	global_load_dword v4, v112, s[0:1]
	s_lshl_b64 s[0:1], s[12:13], 14
	s_add_u32 s80, s91, s0
	s_addc_u32 s81, s54, s1
	s_lshl_b32 s0, s50, 12
	s_mov_b32 s1, s4
	s_lshl_b64 s[0:1], s[0:1], 2
	v_div_fmas_f32 v2, v2, v3, v5
	s_add_u32 s12, s91, s0
	v_div_fixup_f32 v0, v2, v0, 1.0
	s_mov_b32 s2, 0
	s_addc_u32 s13, s54, s1
	v_mov_b32_e32 v2, 0
	v_mov_b32_e32 v3, 0
	v_readlane_b32 s17, v254, 11
	v_readlane_b32 s18, v254, 12
	v_readlane_b32 s19, v254, 13
	v_readlane_b32 s20, v254, 14
	v_readlane_b32 s21, v254, 15
	v_readlane_b32 s24, v254, 18
	v_readlane_b32 s25, v254, 19
	v_readlane_b32 s26, v254, 20
	v_readlane_b32 s27, v254, 21
	v_readlane_b32 s28, v254, 22
	v_readlane_b32 s29, v254, 23
	v_readlane_b32 s30, v254, 24
	v_readlane_b32 s31, v254, 25
	s_movk_i32 s3, 0x5eed
	s_sub_u32 s0, s12, s80
	v_lshlrev_b32_e32 v248, 4, v192
	v_sub_u32_e32 v213, 0x1000, v248
	v_sub_u32_e32 v249, 0, v213
	v_max_i32_e32 v249, v213, v249
	v_ashrrev_i32_e32 v250, 31, v213
	v_and_b32_e32 v250, s0, v250
	v_lshl_add_u32 v249, v249, 2, v250
	global_load_dword v95, v249, s[80:81]
	v_add_u32_e32 v214, -1, v213
	v_sub_u32_e32 v249, 0, v214
	v_max_i32_e32 v249, v214, v249
	v_ashrrev_i32_e32 v250, 31, v214
	v_and_b32_e32 v250, s0, v250
	v_lshl_add_u32 v249, v249, 2, v250
	global_load_dword v96, v249, s[80:81]
	v_add_u32_e32 v215, -2, v213
	v_sub_u32_e32 v249, 0, v215
	v_max_i32_e32 v249, v215, v249
	v_ashrrev_i32_e32 v250, 31, v215
	v_and_b32_e32 v250, s0, v250
	v_lshl_add_u32 v249, v249, 2, v250
	global_load_dword v97, v249, s[80:81]
	v_add_u32_e32 v216, -3, v213
	v_sub_u32_e32 v249, 0, v216
	v_max_i32_e32 v249, v216, v249
	v_ashrrev_i32_e32 v250, 31, v216
	v_and_b32_e32 v250, s0, v250
	v_lshl_add_u32 v249, v249, 2, v250
	global_load_dword v98, v249, s[80:81]
	v_add_u32_e32 v217, -4, v213
	v_sub_u32_e32 v249, 0, v217
	v_max_i32_e32 v249, v217, v249
	v_ashrrev_i32_e32 v250, 31, v217
	v_and_b32_e32 v250, s0, v250
	v_lshl_add_u32 v249, v249, 2, v250
	global_load_dword v99, v249, s[80:81]
	v_add_u32_e32 v218, -5, v213
	v_sub_u32_e32 v249, 0, v218
	v_max_i32_e32 v249, v218, v249
	v_ashrrev_i32_e32 v250, 31, v218
	v_and_b32_e32 v250, s0, v250
	v_lshl_add_u32 v249, v249, 2, v250
	global_load_dword v100, v249, s[80:81]
	v_add_u32_e32 v219, -6, v213
	v_sub_u32_e32 v249, 0, v219
	v_max_i32_e32 v249, v219, v249
	v_ashrrev_i32_e32 v250, 31, v219
	v_and_b32_e32 v250, s0, v250
	v_lshl_add_u32 v249, v249, 2, v250
	global_load_dword v101, v249, s[80:81]
	v_add_u32_e32 v220, -7, v213
	v_sub_u32_e32 v249, 0, v220
	v_max_i32_e32 v249, v220, v249
	v_ashrrev_i32_e32 v250, 31, v220
	v_and_b32_e32 v250, s0, v250
	v_lshl_add_u32 v249, v249, 2, v250
	global_load_dword v102, v249, s[80:81]
	v_add_u32_e32 v221, -8, v213
	v_sub_u32_e32 v249, 0, v221
	v_max_i32_e32 v249, v221, v249
	v_ashrrev_i32_e32 v250, 31, v221
	v_and_b32_e32 v250, s0, v250
	v_lshl_add_u32 v249, v249, 2, v250
	global_load_dword v103, v249, s[80:81]
	v_add_u32_e32 v222, -9, v213
	v_sub_u32_e32 v249, 0, v222
	v_max_i32_e32 v249, v222, v249
	v_ashrrev_i32_e32 v250, 31, v222
	v_and_b32_e32 v250, s0, v250
	v_lshl_add_u32 v249, v249, 2, v250
	global_load_dword v104, v249, s[80:81]
	v_add_u32_e32 v223, -10, v213
	v_sub_u32_e32 v249, 0, v223
	v_max_i32_e32 v249, v223, v249
	v_ashrrev_i32_e32 v250, 31, v223
	v_and_b32_e32 v250, s0, v250
	v_lshl_add_u32 v249, v249, 2, v250
	global_load_dword v105, v249, s[80:81]
	v_add_u32_e32 v224, -11, v213
	v_sub_u32_e32 v249, 0, v224
	v_max_i32_e32 v249, v224, v249
	v_ashrrev_i32_e32 v250, 31, v224
	v_and_b32_e32 v250, s0, v250
	v_lshl_add_u32 v249, v249, 2, v250
	global_load_dword v106, v249, s[80:81]
	v_add_u32_e32 v225, -12, v213
	v_sub_u32_e32 v249, 0, v225
	v_max_i32_e32 v249, v225, v249
	v_ashrrev_i32_e32 v250, 31, v225
	v_and_b32_e32 v250, s0, v250
	v_lshl_add_u32 v249, v249, 2, v250
	global_load_dword v107, v249, s[80:81]
	v_add_u32_e32 v226, -13, v213
	v_sub_u32_e32 v249, 0, v226
	v_max_i32_e32 v249, v226, v249
	v_ashrrev_i32_e32 v250, 31, v226
	v_and_b32_e32 v250, s0, v250
	v_lshl_add_u32 v249, v249, 2, v250
	global_load_dword v108, v249, s[80:81]
	v_add_u32_e32 v227, -14, v213
	v_sub_u32_e32 v249, 0, v227
	v_max_i32_e32 v249, v227, v249
	v_ashrrev_i32_e32 v250, 31, v227
	v_and_b32_e32 v250, s0, v250
	v_lshl_add_u32 v249, v249, 2, v250
	global_load_dword v109, v249, s[80:81]
	v_add_u32_e32 v228, -15, v213
	v_sub_u32_e32 v249, 0, v228
	v_max_i32_e32 v249, v228, v249
	v_ashrrev_i32_e32 v250, 31, v228
	v_and_b32_e32 v250, s0, v250
	v_lshl_add_u32 v249, v249, 2, v250
	global_load_dword v110, v249, s[80:81]
	v_add_u32_e32 v229, -16, v213
	v_sub_u32_e32 v249, 0, v229
	v_max_i32_e32 v249, v229, v249
	v_ashrrev_i32_e32 v250, 31, v229
	v_and_b32_e32 v250, s0, v250
	v_lshl_add_u32 v249, v249, 2, v250
	global_load_dword v111, v249, s[80:81]
	v_add_u32_e32 v230, -17, v213
	v_sub_u32_e32 v249, 0, v230
	v_max_i32_e32 v249, v230, v249
	v_ashrrev_i32_e32 v250, 31, v230
	v_and_b32_e32 v250, s0, v250
	v_lshl_add_u32 v249, v249, 2, v250
	global_load_dword v122, v249, s[80:81]
	v_add_u32_e32 v231, -18, v213
	v_sub_u32_e32 v249, 0, v231
	v_max_i32_e32 v249, v231, v249
	v_ashrrev_i32_e32 v250, 31, v231
	v_and_b32_e32 v250, s0, v250
	v_lshl_add_u32 v249, v249, 2, v250
	global_load_dword v123, v249, s[80:81]
	v_add_u32_e32 v232, -19, v213
	v_sub_u32_e32 v249, 0, v232
	v_max_i32_e32 v249, v232, v249
	v_ashrrev_i32_e32 v250, 31, v232
	v_and_b32_e32 v250, s0, v250
	v_lshl_add_u32 v249, v249, 2, v250
	global_load_dword v124, v249, s[80:81]
	v_add_u32_e32 v233, -20, v213
	v_sub_u32_e32 v249, 0, v233
	v_max_i32_e32 v249, v233, v249
	v_ashrrev_i32_e32 v250, 31, v233
	v_and_b32_e32 v250, s0, v250
	v_lshl_add_u32 v249, v249, 2, v250
	global_load_dword v125, v249, s[80:81]
	v_add_u32_e32 v234, -21, v213
	v_sub_u32_e32 v249, 0, v234
	v_max_i32_e32 v249, v234, v249
	v_ashrrev_i32_e32 v250, 31, v234
	v_and_b32_e32 v250, s0, v250
	v_lshl_add_u32 v249, v249, 2, v250
	global_load_dword v126, v249, s[80:81]
	v_add_u32_e32 v235, -22, v213
	v_sub_u32_e32 v249, 0, v235
	v_max_i32_e32 v249, v235, v249
	v_ashrrev_i32_e32 v250, 31, v235
	v_and_b32_e32 v250, s0, v250
	v_lshl_add_u32 v249, v249, 2, v250
	global_load_dword v127, v249, s[80:81]
	global_load_dword v246, v112, s[80:81]
	global_load_dword v247, v112, s[12:13]
	v_lshlrev_b32_e32 v251, 5, v192
	v_add_u32_e32 v162, 0x10040, v251
	s_waitcnt vmcnt(0)
	v_mul_f32_e32 v246, v0, v246
	v_mul_f32_e32 v247, v1, v247
	v_add_f32_e32 v246, v246, v247
	v_add_f32_e32 v246, v4, v246
	v_cmp_lt_i32_e32 vcc, 0, v213
	v_add_u32_e32 v249, 0xfff, v213
	s_nop 0
	v_cndmask_b32_e32 v248, v1, v0, vcc
	v_cmp_eq_u32_e32 vcc, 0, v213
	v_mul_f32_e32 v95, v248, v95
	s_nop 0
	v_cndmask_b32_e32 v95, v95, v246, vcc
	v_cmp_gt_u32_e32 vcc, 0x1fff, v249
	s_nop 1
	v_cndmask_b32_e32 v95, 0, v95, vcc
	v_cmp_lt_i32_e32 vcc, 0, v214
	v_add_u32_e32 v249, 0xfff, v214
	s_nop 0
	v_cndmask_b32_e32 v248, v1, v0, vcc
	v_cmp_eq_u32_e32 vcc, 0, v214
	v_mul_f32_e32 v96, v248, v96
	s_nop 0
	v_cndmask_b32_e32 v96, v96, v246, vcc
	v_cmp_gt_u32_e32 vcc, 0x1fff, v249
	s_nop 1
	v_cndmask_b32_e32 v96, 0, v96, vcc
	v_cmp_lt_i32_e32 vcc, 0, v215
	v_add_u32_e32 v249, 0xfff, v215
	s_nop 0
	v_cndmask_b32_e32 v248, v1, v0, vcc
	v_cmp_eq_u32_e32 vcc, 0, v215
	v_mul_f32_e32 v97, v248, v97
	s_nop 0
	v_cndmask_b32_e32 v97, v97, v246, vcc
	v_cmp_gt_u32_e32 vcc, 0x1fff, v249
	s_nop 1
	v_cndmask_b32_e32 v97, 0, v97, vcc
	v_cmp_lt_i32_e32 vcc, 0, v216
	v_add_u32_e32 v249, 0xfff, v216
	s_nop 0
	v_cndmask_b32_e32 v248, v1, v0, vcc
	v_cmp_eq_u32_e32 vcc, 0, v216
	v_mul_f32_e32 v98, v248, v98
	s_nop 0
	v_cndmask_b32_e32 v98, v98, v246, vcc
	v_cmp_gt_u32_e32 vcc, 0x1fff, v249
	s_nop 1
	v_cndmask_b32_e32 v98, 0, v98, vcc
	v_cmp_lt_i32_e32 vcc, 0, v217
	v_add_u32_e32 v249, 0xfff, v217
	s_nop 0
	v_cndmask_b32_e32 v248, v1, v0, vcc
	v_cmp_eq_u32_e32 vcc, 0, v217
	v_mul_f32_e32 v99, v248, v99
	s_nop 0
	v_cndmask_b32_e32 v99, v99, v246, vcc
	v_cmp_gt_u32_e32 vcc, 0x1fff, v249
	s_nop 1
	v_cndmask_b32_e32 v99, 0, v99, vcc
	v_cmp_lt_i32_e32 vcc, 0, v218
	v_add_u32_e32 v249, 0xfff, v218
	s_nop 0
	v_cndmask_b32_e32 v248, v1, v0, vcc
	v_cmp_eq_u32_e32 vcc, 0, v218
	v_mul_f32_e32 v100, v248, v100
	s_nop 0
	v_cndmask_b32_e32 v100, v100, v246, vcc
	v_cmp_gt_u32_e32 vcc, 0x1fff, v249
	s_nop 1
	v_cndmask_b32_e32 v100, 0, v100, vcc
	v_cmp_lt_i32_e32 vcc, 0, v219
	v_add_u32_e32 v249, 0xfff, v219
	s_nop 0
	v_cndmask_b32_e32 v248, v1, v0, vcc
	v_cmp_eq_u32_e32 vcc, 0, v219
	v_mul_f32_e32 v101, v248, v101
	s_nop 0
	v_cndmask_b32_e32 v101, v101, v246, vcc
	v_cmp_gt_u32_e32 vcc, 0x1fff, v249
	s_nop 1
	v_cndmask_b32_e32 v101, 0, v101, vcc
	v_cmp_lt_i32_e32 vcc, 0, v220
	v_add_u32_e32 v249, 0xfff, v220
	s_nop 0
	v_cndmask_b32_e32 v248, v1, v0, vcc
	v_cmp_eq_u32_e32 vcc, 0, v220
	v_mul_f32_e32 v102, v248, v102
	s_nop 0
	v_cndmask_b32_e32 v102, v102, v246, vcc
	v_cmp_gt_u32_e32 vcc, 0x1fff, v249
	s_nop 1
	v_cndmask_b32_e32 v102, 0, v102, vcc
	v_cmp_lt_i32_e32 vcc, 0, v221
	v_add_u32_e32 v249, 0xfff, v221
	s_nop 0
	v_cndmask_b32_e32 v248, v1, v0, vcc
	v_cmp_eq_u32_e32 vcc, 0, v221
	v_mul_f32_e32 v103, v248, v103
	s_nop 0
	v_cndmask_b32_e32 v103, v103, v246, vcc
	v_cmp_gt_u32_e32 vcc, 0x1fff, v249
	s_nop 1
	v_cndmask_b32_e32 v103, 0, v103, vcc
	v_cmp_lt_i32_e32 vcc, 0, v222
	v_add_u32_e32 v249, 0xfff, v222
	s_nop 0
	v_cndmask_b32_e32 v248, v1, v0, vcc
	v_cmp_eq_u32_e32 vcc, 0, v222
	v_mul_f32_e32 v104, v248, v104
	s_nop 0
	v_cndmask_b32_e32 v104, v104, v246, vcc
	v_cmp_gt_u32_e32 vcc, 0x1fff, v249
	s_nop 1
	v_cndmask_b32_e32 v104, 0, v104, vcc
	v_cmp_lt_i32_e32 vcc, 0, v223
	v_add_u32_e32 v249, 0xfff, v223
	s_nop 0
	v_cndmask_b32_e32 v248, v1, v0, vcc
	v_cmp_eq_u32_e32 vcc, 0, v223
	v_mul_f32_e32 v105, v248, v105
	s_nop 0
	v_cndmask_b32_e32 v105, v105, v246, vcc
	v_cmp_gt_u32_e32 vcc, 0x1fff, v249
	s_nop 1
	v_cndmask_b32_e32 v105, 0, v105, vcc
	v_cmp_lt_i32_e32 vcc, 0, v224
	v_add_u32_e32 v249, 0xfff, v224
	s_nop 0
	v_cndmask_b32_e32 v248, v1, v0, vcc
	v_cmp_eq_u32_e32 vcc, 0, v224
	v_mul_f32_e32 v106, v248, v106
	s_nop 0
	v_cndmask_b32_e32 v106, v106, v246, vcc
	v_cmp_gt_u32_e32 vcc, 0x1fff, v249
	s_nop 1
	v_cndmask_b32_e32 v106, 0, v106, vcc
	v_cmp_lt_i32_e32 vcc, 0, v225
	v_add_u32_e32 v249, 0xfff, v225
	s_nop 0
	v_cndmask_b32_e32 v248, v1, v0, vcc
	v_cmp_eq_u32_e32 vcc, 0, v225
	v_mul_f32_e32 v107, v248, v107
	s_nop 0
	v_cndmask_b32_e32 v107, v107, v246, vcc
	v_cmp_gt_u32_e32 vcc, 0x1fff, v249
	s_nop 1
	v_cndmask_b32_e32 v107, 0, v107, vcc
	v_cmp_lt_i32_e32 vcc, 0, v226
	v_add_u32_e32 v249, 0xfff, v226
	s_nop 0
	v_cndmask_b32_e32 v248, v1, v0, vcc
	v_cmp_eq_u32_e32 vcc, 0, v226
	v_mul_f32_e32 v108, v248, v108
	s_nop 0
	v_cndmask_b32_e32 v108, v108, v246, vcc
	v_cmp_gt_u32_e32 vcc, 0x1fff, v249
	s_nop 1
	v_cndmask_b32_e32 v108, 0, v108, vcc
	v_cmp_lt_i32_e32 vcc, 0, v227
	v_add_u32_e32 v249, 0xfff, v227
	s_nop 0
	v_cndmask_b32_e32 v248, v1, v0, vcc
	v_cmp_eq_u32_e32 vcc, 0, v227
	v_mul_f32_e32 v109, v248, v109
	s_nop 0
	v_cndmask_b32_e32 v109, v109, v246, vcc
	v_cmp_gt_u32_e32 vcc, 0x1fff, v249
	s_nop 1
	v_cndmask_b32_e32 v109, 0, v109, vcc
	v_cmp_lt_i32_e32 vcc, 0, v228
	v_add_u32_e32 v249, 0xfff, v228
	s_nop 0
	v_cndmask_b32_e32 v248, v1, v0, vcc
	v_cmp_eq_u32_e32 vcc, 0, v228
	v_mul_f32_e32 v110, v248, v110
	s_nop 0
	v_cndmask_b32_e32 v110, v110, v246, vcc
	v_cmp_gt_u32_e32 vcc, 0x1fff, v249
	s_nop 1
	v_cndmask_b32_e32 v110, 0, v110, vcc
	v_cmp_lt_i32_e32 vcc, 0, v229
	v_add_u32_e32 v249, 0xfff, v229
	s_nop 0
	v_cndmask_b32_e32 v248, v1, v0, vcc
	v_cmp_eq_u32_e32 vcc, 0, v229
	v_mul_f32_e32 v111, v248, v111
	s_nop 0
	v_cndmask_b32_e32 v111, v111, v246, vcc
	v_cmp_gt_u32_e32 vcc, 0x1fff, v249
	s_nop 1
	v_cndmask_b32_e32 v111, 0, v111, vcc
	v_cmp_lt_i32_e32 vcc, 0, v230
	v_add_u32_e32 v249, 0xfff, v230
	s_nop 0
	v_cndmask_b32_e32 v248, v1, v0, vcc
	v_cmp_eq_u32_e32 vcc, 0, v230
	v_mul_f32_e32 v122, v248, v122
	s_nop 0
	v_cndmask_b32_e32 v122, v122, v246, vcc
	v_cmp_gt_u32_e32 vcc, 0x1fff, v249
	s_nop 1
	v_cndmask_b32_e32 v122, 0, v122, vcc
	v_cmp_lt_i32_e32 vcc, 0, v231
	v_add_u32_e32 v249, 0xfff, v231
	s_nop 0
	v_cndmask_b32_e32 v248, v1, v0, vcc
	v_cmp_eq_u32_e32 vcc, 0, v231
	v_mul_f32_e32 v123, v248, v123
	s_nop 0
	v_cndmask_b32_e32 v123, v123, v246, vcc
	v_cmp_gt_u32_e32 vcc, 0x1fff, v249
	s_nop 1
	v_cndmask_b32_e32 v123, 0, v123, vcc
	v_cmp_lt_i32_e32 vcc, 0, v232
	v_add_u32_e32 v249, 0xfff, v232
	s_nop 0
	v_cndmask_b32_e32 v248, v1, v0, vcc
	v_cmp_eq_u32_e32 vcc, 0, v232
	v_mul_f32_e32 v124, v248, v124
	s_nop 0
	v_cndmask_b32_e32 v124, v124, v246, vcc
	v_cmp_gt_u32_e32 vcc, 0x1fff, v249
	s_nop 1
	v_cndmask_b32_e32 v124, 0, v124, vcc
	v_cmp_lt_i32_e32 vcc, 0, v233
	v_add_u32_e32 v249, 0xfff, v233
	s_nop 0
	v_cndmask_b32_e32 v248, v1, v0, vcc
	v_cmp_eq_u32_e32 vcc, 0, v233
	v_mul_f32_e32 v125, v248, v125
	s_nop 0
	v_cndmask_b32_e32 v125, v125, v246, vcc
	v_cmp_gt_u32_e32 vcc, 0x1fff, v249
	s_nop 1
	v_cndmask_b32_e32 v125, 0, v125, vcc
	v_cmp_lt_i32_e32 vcc, 0, v234
	v_add_u32_e32 v249, 0xfff, v234
	s_nop 0
	v_cndmask_b32_e32 v248, v1, v0, vcc
	v_cmp_eq_u32_e32 vcc, 0, v234
	v_mul_f32_e32 v126, v248, v126
	s_nop 0
	v_cndmask_b32_e32 v126, v126, v246, vcc
	v_cmp_gt_u32_e32 vcc, 0x1fff, v249
	s_nop 1
	v_cndmask_b32_e32 v126, 0, v126, vcc
	v_cmp_lt_i32_e32 vcc, 0, v235
	v_add_u32_e32 v249, 0xfff, v235
	s_nop 0
	v_cndmask_b32_e32 v248, v1, v0, vcc
	v_cmp_eq_u32_e32 vcc, 0, v235
	v_mul_f32_e32 v127, v248, v127
	s_nop 0
	v_cndmask_b32_e32 v127, v127, v246, vcc
	v_cmp_gt_u32_e32 vcc, 0x1fff, v249
	s_nop 1
	v_cndmask_b32_e32 v127, 0, v127, vcc
	v_cvt_pk_bf16_f32 v142, v95, v96
	v_cvt_pk_bf16_f32 v143, v97, v98
	v_cvt_pk_bf16_f32 v144, v99, v100
	v_cvt_pk_bf16_f32 v145, v101, v102
	v_cvt_pk_bf16_f32 v146, v103, v104
	v_cvt_pk_bf16_f32 v147, v105, v106
	v_cvt_pk_bf16_f32 v148, v107, v108
	v_cvt_pk_bf16_f32 v149, v109, v110
	v_cvt_pk_bf16_f32 v150, v111, v122
	v_cvt_pk_bf16_f32 v151, v123, v124
	v_cvt_pk_bf16_f32 v152, v97, v98
	v_cvt_pk_bf16_f32 v153, v99, v100
	v_cvt_pk_bf16_f32 v154, v101, v102
	v_cvt_pk_bf16_f32 v155, v103, v104
	v_cvt_pk_bf16_f32 v156, v105, v106
	v_cvt_pk_bf16_f32 v157, v107, v108
	v_cvt_pk_bf16_f32 v158, v109, v110
	v_cvt_pk_bf16_f32 v159, v111, v122
	v_cvt_pk_bf16_f32 v160, v123, v124
	v_cvt_pk_bf16_f32 v161, v125, v126
	v_cvt_pk_bf16_f32 v236, v96, v97
	v_cvt_pk_bf16_f32 v237, v98, v99
	v_cvt_pk_bf16_f32 v238, v100, v101
	v_cvt_pk_bf16_f32 v239, v102, v103
	v_cvt_pk_bf16_f32 v240, v104, v105
	v_cvt_pk_bf16_f32 v241, v106, v107
	v_cvt_pk_bf16_f32 v242, v108, v109
	v_cvt_pk_bf16_f32 v243, v110, v111
	v_cvt_pk_bf16_f32 v244, v122, v123
	v_cvt_pk_bf16_f32 v245, v124, v125
	v_cvt_pk_bf16_f32 v170, v98, v99
	v_cvt_pk_bf16_f32 v171, v100, v101
	v_cvt_pk_bf16_f32 v172, v102, v103
	v_cvt_pk_bf16_f32 v173, v104, v105
	v_cvt_pk_bf16_f32 v174, v106, v107
	v_cvt_pk_bf16_f32 v175, v108, v109
	v_cvt_pk_bf16_f32 v176, v110, v111
	v_cvt_pk_bf16_f32 v177, v122, v123
	v_cvt_pk_bf16_f32 v178, v124, v125
	v_cvt_pk_bf16_f32 v179, v126, v127
	ds_write_b128 v251, v[142:145] offset:0
	ds_write_b128 v251, v[146:149] offset:16
	ds_write_b128 v251, v[236:239] offset:16400
	ds_write_b128 v251, v[240:243] offset:16416
	ds_write_b128 v251, v[152:155] offset:32800
	ds_write_b128 v251, v[156:159] offset:32816
	ds_write_b128 v251, v[170:173] offset:49200
	ds_write_b128 v251, v[174:177] offset:49216
	ds_write_b128 v162, v[144:147] offset:0
	ds_write_b128 v162, v[148:151] offset:16
	ds_write_b128 v162, v[238:241] offset:16400
	ds_write_b128 v162, v[242:245] offset:16416
	ds_write_b128 v162, v[154:157] offset:32800
	ds_write_b128 v162, v[158:161] offset:32816
	ds_write_b128 v162, v[172:175] offset:49200
	ds_write_b128 v162, v[176:179] offset:49216
	s_andn2_b64 vcc, exec, s[88:89]
	s_cbranch_vccnz .LBB0_721
	global_load_dwordx4 v[0:3], v[56:57], off
	v_add_u32_e32 v4, v17, v67
	s_waitcnt vmcnt(0)
	ds_write_b128 v4, v[0:3]
	global_load_dwordx4 v[0:3], v[58:59], off
	v_add_u32_e32 v4, v17, v66
	s_waitcnt vmcnt(0)
	ds_write_b128 v4, v[0:3]
